# gi
# speedup vs baseline: 1.0070x; 1.0025x over previous
; #define STAGE_B(b, h, kt)                                                                             \
;   _Pragma("unroll") for (int _i = 0; _i < 2; ++_i)                                                    \
;       gload_lds16((const char*)(Bb + (size_t)((h) * 128 + _i * 64) * ldb + (kt) * 64) + (size_t)bov0,  \
;                   G_SB(b, h) + tid * 16 + _i * 8192)
; template <bool GATHER, class AO>
; DEVI void gemm_prologue(const u16* __restrict__ Ab, int lda, AO aoff, const u16* __restrict__ Bb, int ldb, int brow,
;                         int bcol, char* shmc, GemmOff& off) {
;   const int tid = opaque_tid();
;   GEMM_OFFSETS;
;   STAGE_B(0, 0, 0); STAGE_A(0, 0, 0);
;   STAGE_B(0, 1, 0); STAGE_A(0, 1, 0);
;   STAGE_B(1, 0, 1); STAGE_A(1, 0, 1); STAGE_B(1, 1, 1);
; DEVI void ph_gateup(const Params& p, char* shm) {
;     ...
;         int e2, brow2, bcol2;
;         dec(nit, e2, brow2, bcol2);
;         auto aoff2 = [&](int rr) {
;           int b = rr >> 9, c = rr & 511;
;           int tok = b * 4096 + seltok[(b * 16 + e2) * 512 + c];
;           return (unsigned)tok * 512u;
;         };
;         gemm_prologue<true>(hb8, 512, aoff2, WGU + (size_t)e2 * 4096 * 512, 512, brow2, bcol2, shm, goff);
.LBB0_1212:
	s_or_b64 exec, exec, s[2:3]
	s_add_i32 s44, s44, s78
	s_nop 7
	s_nop 7
	s_nop 7
	s_cmpk_gt_i32 s44, 0xfff
	s_cselect_b64 s[2:3], -1, 0
	s_and_b64 vcc, exec, s[2:3]
	s_cbranch_vccnz .LBB0_1181
	v_mov_b32_e32 v0, v214
	s_lshl_b32 s6, s44, 1
	v_ashrrev_i32_e32 v1, 31, v0
	v_lshrrev_b32_e32 v1, 26, v1
	v_lshlrev_b32_e32 v4, 4, v0
	v_add_u32_e32 v1, v0, v1
	v_bfe_i32 v0, v0, 27, 1
	v_lshrrev_b32_e32 v0, 22, v0
	v_add_u32_e32 v0, v4, v0
	v_and_b32_e32 v0, 0xfffffc00, v0
	v_sub_u32_e32 v0, v4, v0
	v_lshrrev_b32_e32 v2, 4, v0
	v_bitop3_b32 v2, v2, v0, 32 bitop3:0x6c
	v_ashrrev_i32_e32 v0, 31, v0
	v_ashrrev_i32_e32 v1, 6, v1
	v_lshrrev_b32_e32 v0, 26, v0
	s_and_b32 s6, s6, 14
	s_ashr_i32 s7, s44, 11
	v_lshlrev_b32_e32 v3, 3, v1
	v_add_u32_e32 v0, v2, v0
	s_add_i32 s28, s6, s7
	s_lshr_b32 s6, s44, 7
	v_and_b32_e32 v3, -16, v3
	v_ashrrev_i32_e32 v0, 6, v0
	s_and_b32 s6, s6, 12
	s_bfe_u32 s7, s44, 0x20003
	s_ashr_i32 s29, s28, 31
	v_add_u32_e32 v3, v0, v3
	v_mul_i32_i24_e32 v0, 64, v0
	s_or_b32 s30, s6, s7
	s_lshl_b64 s[6:7], s[28:29], 22
	v_readlane_b32 s29, v242, 42
	v_sub_u32_e32 v0, v2, v0
	s_add_u32 s6, s29, s6
	v_readlane_b32 s29, v241, 4
	v_lshlrev_b32_e32 v1, 5, v1
	v_ashrrev_i16_sdwa v0, v217, sext(v0) dst_sel:DWORD dst_unused:UNUSED_PAD src0_sel:DWORD src1_sel:BYTE_0
	v_lshl_add_u32 v5, s30, 8, v3
	s_addc_u32 s7, s29, s7
	v_and_b32_e32 v1, 32, v1
	v_bfe_i32 v0, v0, 0, 16
	s_lshl_b32 s28, s28, 9
	v_add_lshl_u32 v2, v1, v0, 1
	v_mov_b32_e32 v244, v5
	v_ashrrev_i32_e32 v252, 9, v244
	v_lshl_add_u32 v243, v252, 13, s28
	v_and_or_b32 v244, v244, s35, v243
	v_ashrrev_i32_e32 v245, 31, v244
	v_lshl_add_u64 v[244:245], v[244:245], 2, s[82:83]
	global_load_dword v244, v[244:245], off
	v_add_u32_e32 v246, 0x80, v5
	v_ashrrev_i32_e32 v253, 9, v246
	v_lshl_add_u32 v243, v253, 13, s28
	v_and_or_b32 v246, v246, s35, v243
	v_ashrrev_i32_e32 v247, 31, v246
	v_lshl_add_u64 v[246:247], v[246:247], 2, s[82:83]
	global_load_dword v246, v[246:247], off
	v_add_u32_e32 v248, 0x40, v5
	v_ashrrev_i32_e32 v254, 9, v248
	v_lshl_add_u32 v243, v254, 13, s28
	v_and_or_b32 v248, v248, s35, v243
	v_ashrrev_i32_e32 v249, 31, v248
	v_lshl_add_u64 v[248:249], v[248:249], 2, s[82:83]
	global_load_dword v248, v[248:249], off
	v_add_u32_e32 v250, 0xc0, v5
	v_ashrrev_i32_e32 v255, 9, v250
	v_lshl_add_u32 v243, v255, 13, s28
	v_and_or_b32 v250, v250, s35, v243
	v_ashrrev_i32_e32 v251, 31, v250
	v_lshl_add_u64 v[250:251], v[250:251], 2, s[82:83]
	global_load_dword v250, v[250:251], off
	s_waitcnt vmcnt(0)
	v_lshlrev_b32_e32 v244, 10, v244
	v_lshlrev_b32_e32 v252, 22, v252
	v_add3_u32 v218, v2, v244, v252
	v_lshlrev_b32_e32 v246, 10, v246
	v_lshlrev_b32_e32 v253, 22, v253
	v_add3_u32 v219, v2, v246, v253
	v_lshlrev_b32_e32 v248, 10, v248
	v_lshlrev_b32_e32 v254, 22, v254
	v_add3_u32 v220, v2, v248, v254
	v_lshlrev_b32_e32 v250, 10, v250
	v_lshlrev_b32_e32 v255, 22, v255
	v_add3_u32 v221, v2, v250, v255
	v_add_u32_e32 v6, s37, v4
	s_lshl_b32 s28, s44, 13
	s_and_b32 s28, s28, 0x3c0000
	v_add_u32_e32 v5, s36, v4
	v_lshlrev_b32_e32 v0, 10, v3
	v_add3_u32 v192, v0, s28, v2
	v_readfirstlane_b32 s28, v5
	s_mov_b32 m0, s28
	v_add_u32_e32 v5, 0x2000, v5
	v_lshl_add_u64 v[0:1], s[6:7], 0, v[192:193]
	global_load_lds_dwordx4 v192, s[6:7]
	v_readfirstlane_b32 s6, v5
	v_lshl_add_u64 v[2:3], v[0:1], 0, s[10:11]
	s_mov_b32 m0, s6
	v_add_u32_e32 v5, 0, v4
	global_load_lds_dwordx4 v[2:3], off
	v_readfirstlane_b32 s6, v5
	v_add_u32_e32 v2, 0x2000, v5
	s_mov_b32 m0, s6
	v_readfirstlane_b32 s6, v2
	global_load_lds_dwordx4 v218, s[76:77]
	s_mov_b32 m0, s6
	v_readfirstlane_b32 s6, v6
	v_add_u32_e32 v6, 0x2000, v6
	global_load_lds_dwordx4 v220, s[76:77]
	v_lshl_add_u64 v[2:3], v[0:1], 0, s[12:13]
	s_mov_b32 m0, s6
	v_readfirstlane_b32 s6, v6
	global_load_lds_dwordx4 v[2:3], off
	v_lshl_add_u64 v[2:3], v[0:1], 0, s[14:15]
	s_mov_b32 m0, s6
	v_add_u32_e32 v6, s38, v4
	global_load_lds_dwordx4 v[2:3], off
	v_add_u32_e32 v2, 0x4000, v5
	v_add_u32_e32 v4, s39, v4
	v_readfirstlane_b32 s6, v2
	v_add_u32_e32 v2, 0x6000, v5
	s_mov_b32 m0, s6
	v_readfirstlane_b32 s6, v2
	global_load_lds_dwordx4 v219, s[76:77]
	s_mov_b32 m0, s6
	v_readfirstlane_b32 s6, v6
	v_add_u32_e32 v6, 0x2000, v6
	global_load_lds_dwordx4 v221, s[76:77]
	v_lshl_add_u64 v[2:3], v[0:1], 0, s[16:17]
	s_mov_b32 m0, s6
	v_readfirstlane_b32 s6, v6
	global_load_lds_dwordx4 v[2:3], off
	v_lshl_add_u64 v[2:3], v[0:1], 0, s[18:19]
	s_mov_b32 m0, s6
	v_mov_b32_e32 v222, v192
	global_load_lds_dwordx4 v[2:3], off
	v_add_u32_e32 v2, 0x8000, v5
	s_nop 0
	v_readfirstlane_b32 s6, v2
	v_add_u32_e32 v2, 0xa000, v5
	s_mov_b32 m0, s6
	v_readfirstlane_b32 s6, v2
	global_load_lds_dwordx4 v218, s[8:9]
	s_mov_b32 m0, s6
	v_readfirstlane_b32 s6, v4
	global_load_lds_dwordx4 v220, s[8:9]
	v_lshl_add_u64 v[2:3], v[0:1], 0, s[20:21]
	s_mov_b32 m0, s6
	v_lshl_add_u64 v[0:1], v[0:1], 0, s[22:23]
	global_load_lds_dwordx4 v[2:3], off
	v_add_u32_e32 v2, 0x2000, v4
	s_nop 0
	v_readfirstlane_b32 s6, v2
	s_mov_b32 m0, s6
	s_nop 0
	global_load_lds_dwordx4 v[0:1], off
	s_branch .LBB0_1181

; #define STAGE_B(b, h, kt)                                                                             \
;   _Pragma("unroll") for (int _i = 0; _i < 2; ++_i)                                                    \
;       gload_lds16((const char*)(Bb + (size_t)((h) * 128 + _i * 64) * ldb + (kt) * 64) + (size_t)bov0,  \
;                   G_SB(b, h) + tid * 16 + _i * 8192)
; template <bool GATHER, class AO>
; DEVI void gemm_prologue(const u16* __restrict__ Ab, int lda, AO aoff, const u16* __restrict__ Bb, int ldb, int brow,
;                         int bcol, char* shmc, GemmOff& off) {
;   const int tid = opaque_tid();
;   GEMM_OFFSETS;
;   STAGE_B(0, 0, 0); STAGE_A(0, 0, 0);
;   STAGE_B(0, 1, 0); STAGE_A(0, 1, 0);
;   STAGE_B(1, 0, 1); STAGE_A(1, 0, 1); STAGE_B(1, 1, 1);
; DEVI void ph_gateup(const Params& p, char* shm) {
;     ...
;         int e2, brow2, bcol2;
;         dec(nit, e2, brow2, bcol2);
;         auto aoff2 = [&](int rr) {
;           int b = rr >> 9, c = rr & 511;
;           int tok = b * 4096 + seltok[(b * 16 + e2) * 512 + c];
;           return (unsigned)tok * 512u;
;         };
;         gemm_prologue<true>(hb8, 512, aoff2, WGU + (size_t)e2 * 4096 * 512, 512, brow2, bcol2, shm, goff);
.LBB0_2048:
	s_or_b64 exec, exec, s[4:5]
	s_add_i32 s61, s61, s78
	s_nop 7
	s_nop 7
	s_nop 7
	s_cmpk_gt_i32 s61, 0xfff
	s_cselect_b64 s[4:5], -1, 0
	s_and_b64 vcc, exec, s[4:5]
	s_cbranch_vccnz .LBB0_2017
	v_mov_b32_e32 v0, v214
	s_lshl_b32 s44, s61, 1
	v_ashrrev_i32_e32 v1, 31, v0
	v_lshrrev_b32_e32 v1, 26, v1
	v_lshlrev_b32_e32 v4, 4, v0
	v_add_u32_e32 v1, v0, v1
	v_bfe_i32 v0, v0, 27, 1
	v_lshrrev_b32_e32 v0, 22, v0
	v_add_u32_e32 v0, v4, v0
	v_and_b32_e32 v0, 0xfffffc00, v0
	v_sub_u32_e32 v0, v4, v0
	v_lshrrev_b32_e32 v2, 4, v0
	v_bitop3_b32 v2, v2, v0, 32 bitop3:0x6c
	v_ashrrev_i32_e32 v0, 31, v0
	v_ashrrev_i32_e32 v1, 6, v1
	v_lshrrev_b32_e32 v0, 26, v0
	s_and_b32 s44, s44, 14
	s_ashr_i32 s45, s61, 11
	v_lshlrev_b32_e32 v3, 3, v1
	v_add_u32_e32 v0, v2, v0
	s_add_i32 s50, s44, s45
	s_lshr_b32 s44, s61, 7
	v_and_b32_e32 v3, -16, v3
	v_ashrrev_i32_e32 v0, 6, v0
	s_and_b32 s44, s44, 12
	s_bfe_u32 s45, s61, 0x20003
	s_ashr_i32 s51, s50, 31
	v_add_u32_e32 v3, v0, v3
	v_mul_i32_i24_e32 v0, 64, v0
	s_or_b32 s52, s44, s45
	s_lshl_b64 s[44:45], s[50:51], 22
	v_readlane_b32 s46, v242, 42
	v_sub_u32_e32 v0, v2, v0
	s_add_u32 s44, s46, s44
	v_readlane_b32 s46, v241, 4
	v_lshlrev_b32_e32 v1, 5, v1
	v_ashrrev_i16_sdwa v0, v217, sext(v0) dst_sel:DWORD dst_unused:UNUSED_PAD src0_sel:DWORD src1_sel:BYTE_0
	v_lshl_add_u32 v5, s52, 8, v3
	s_addc_u32 s45, s46, s45
	v_and_b32_e32 v1, 32, v1
	v_bfe_i32 v0, v0, 0, 16
	s_lshl_b32 s50, s50, 9
	v_add_lshl_u32 v2, v1, v0, 1
	v_mov_b32_e32 v244, v5
	v_ashrrev_i32_e32 v252, 9, v244
	v_lshl_add_u32 v243, v252, 13, s50
	v_and_or_b32 v244, v244, s55, v243
	v_ashrrev_i32_e32 v245, 31, v244
	v_lshl_add_u64 v[244:245], v[244:245], 2, s[82:83]
	global_load_dword v244, v[244:245], off
	v_add_u32_e32 v246, 0x80, v5
	v_ashrrev_i32_e32 v253, 9, v246
	v_lshl_add_u32 v243, v253, 13, s50
	v_and_or_b32 v246, v246, s55, v243
	v_ashrrev_i32_e32 v247, 31, v246
	v_lshl_add_u64 v[246:247], v[246:247], 2, s[82:83]
	global_load_dword v246, v[246:247], off
	v_add_u32_e32 v248, 0x40, v5
	v_ashrrev_i32_e32 v254, 9, v248
	v_lshl_add_u32 v243, v254, 13, s50
	v_and_or_b32 v248, v248, s55, v243
	v_ashrrev_i32_e32 v249, 31, v248
	v_lshl_add_u64 v[248:249], v[248:249], 2, s[82:83]
	global_load_dword v248, v[248:249], off
	v_add_u32_e32 v250, 0xc0, v5
	v_ashrrev_i32_e32 v255, 9, v250
	v_lshl_add_u32 v243, v255, 13, s50
	v_and_or_b32 v250, v250, s55, v243
	v_ashrrev_i32_e32 v251, 31, v250
	v_lshl_add_u64 v[250:251], v[250:251], 2, s[82:83]
	global_load_dword v250, v[250:251], off
	s_waitcnt vmcnt(0)
	v_lshlrev_b32_e32 v244, 10, v244
	v_lshlrev_b32_e32 v252, 22, v252
	v_add3_u32 v218, v2, v244, v252
	v_lshlrev_b32_e32 v246, 10, v246
	v_lshlrev_b32_e32 v253, 22, v253
	v_add3_u32 v219, v2, v246, v253
	v_lshlrev_b32_e32 v248, 10, v248
	v_lshlrev_b32_e32 v254, 22, v254
	v_add3_u32 v220, v2, v248, v254
	v_lshlrev_b32_e32 v250, 10, v250
	v_lshlrev_b32_e32 v255, 22, v255
	v_add3_u32 v221, v2, v250, v255
	v_add_u32_e32 v6, s57, v4
	s_lshl_b32 s50, s61, 13
	s_and_b32 s50, s50, 0x3c0000
	v_add_u32_e32 v5, s56, v4
	v_lshlrev_b32_e32 v0, 10, v3
	v_add3_u32 v192, v0, s50, v2
	v_readfirstlane_b32 s50, v5
	s_mov_b32 m0, s50
	v_add_u32_e32 v5, 0x2000, v5
	v_lshl_add_u64 v[0:1], s[44:45], 0, v[192:193]
	global_load_lds_dwordx4 v192, s[44:45]
	v_readfirstlane_b32 s44, v5
	v_lshl_add_u64 v[2:3], v[0:1], 0, s[6:7]
	s_mov_b32 m0, s44
	v_add_u32_e32 v5, 0, v4
	global_load_lds_dwordx4 v[2:3], off
	v_readfirstlane_b32 s44, v5
	v_add_u32_e32 v2, 0x2000, v5
	s_mov_b32 m0, s44
	v_readfirstlane_b32 s44, v2
	global_load_lds_dwordx4 v218, s[76:77]
	s_mov_b32 m0, s44
	v_readfirstlane_b32 s44, v6
	v_add_u32_e32 v6, 0x2000, v6
	global_load_lds_dwordx4 v220, s[76:77]
	v_lshl_add_u64 v[2:3], v[0:1], 0, s[8:9]
	s_mov_b32 m0, s44
	v_readfirstlane_b32 s44, v6
	global_load_lds_dwordx4 v[2:3], off
	v_lshl_add_u64 v[2:3], v[0:1], 0, s[10:11]
	s_mov_b32 m0, s44
	v_add_u32_e32 v6, s58, v4
	global_load_lds_dwordx4 v[2:3], off
	v_add_u32_e32 v2, 0x4000, v5
	v_add_u32_e32 v4, s59, v4
	v_readfirstlane_b32 s44, v2
	v_add_u32_e32 v2, 0x6000, v5
	s_mov_b32 m0, s44
	v_readfirstlane_b32 s44, v2
	global_load_lds_dwordx4 v219, s[76:77]
	s_mov_b32 m0, s44
	v_readfirstlane_b32 s44, v6
	v_add_u32_e32 v6, 0x2000, v6
	global_load_lds_dwordx4 v221, s[76:77]
	v_lshl_add_u64 v[2:3], v[0:1], 0, s[12:13]
	s_mov_b32 m0, s44
	v_readfirstlane_b32 s44, v6
	global_load_lds_dwordx4 v[2:3], off
	v_lshl_add_u64 v[2:3], v[0:1], 0, s[14:15]
	s_mov_b32 m0, s44
	v_mov_b32_e32 v222, v192
	global_load_lds_dwordx4 v[2:3], off
	v_add_u32_e32 v2, 0x8000, v5
	s_nop 0
	v_readfirstlane_b32 s44, v2
	v_add_u32_e32 v2, 0xa000, v5
	s_mov_b32 m0, s44
	v_readfirstlane_b32 s44, v2
	global_load_lds_dwordx4 v218, s[2:3]
	s_mov_b32 m0, s44
	v_readfirstlane_b32 s44, v4
	global_load_lds_dwordx4 v220, s[2:3]
	v_lshl_add_u64 v[2:3], v[0:1], 0, s[16:17]
	s_mov_b32 m0, s44
	v_lshl_add_u64 v[0:1], v[0:1], 0, s[18:19]
	global_load_lds_dwordx4 v[2:3], off
	v_add_u32_e32 v2, 0x2000, v4
	s_nop 0
	v_readfirstlane_b32 s44, v2
	s_mov_b32 m0, s44
	s_nop 0
	global_load_lds_dwordx4 v[0:1], off
	s_branch .LBB0_2017
